# attention loop: coarser counted LDS waits (9 s_waitcnt per half instead of 24), on top of v019
# baseline (speedup 1.0000x reference)
; #define LAS __attribute__((address_space(3)))
; #define MFMA32(a, b, c) __builtin_amdgcn_mfma_f32_32x32x16_bf16((a), (b), (c), 0, 0, 0)
; template <int MODE> ...
;     ...
;         { const LAS unsigned char* ka = KT + (32 * nt + ql) * KT_PITCH + 16 * half;
; #pragma unroll
;           for (int kg = 0; kg < 2; ++kg) { bf16x8 kf[4];
; #pragma unroll
;               for (int ks = 0; ks < 4; ++ks) kf[ks] = *(const LAS bf16x8*)(ka + 32 * (4 * kg + ks));
; #pragma unroll
;               for (int ks = 0; ks < 4; ++ks) st = MFMA32(kf[ks], qf[4 * kg + ks], st); } }
.LBB0_2107:
	s_lshl_b32 s26, s63, 5
	s_cmp_lg_u32 s63, 0
	s_cbranch_scc1 .Lattn_kready
	v_or_b32_e32 v16, s26, v227
	v_mad_u32_u24 v16, v16, s54, v2
	ds_read_b128 v[82:85], v16
	ds_read_b128 v[86:89], v16 offset:32
	ds_read_b128 v[90:93], v16 offset:64
	ds_read_b128 v[94:97], v16 offset:96
	ds_read_b128 v[98:101], v16 offset:128
	ds_read_b128 v[102:105], v16 offset:160
	ds_read_b128 v[106:109], v16 offset:192
	ds_read_b128 v[110:113], v16 offset:224
	s_waitcnt lgkmcnt(6)
	v_mfma_f32_32x32x16_bf16 v[146:161], v[82:85], v[166:169], 0
	v_mfma_f32_32x32x16_bf16 v[146:161], v[86:89], v[162:165], v[146:161]
	s_waitcnt lgkmcnt(3)
	v_mfma_f32_32x32x16_bf16 v[146:161], v[90:93], v[174:177], v[146:161]
	v_mfma_f32_32x32x16_bf16 v[146:161], v[94:97], v[170:173], v[146:161]
	v_mfma_f32_32x32x16_bf16 v[146:161], v[98:101], v[182:185], v[146:161]
	s_waitcnt lgkmcnt(0)
	v_mfma_f32_32x32x16_bf16 v[146:161], v[102:105], v[178:181], v[146:161]
	v_mfma_f32_32x32x16_bf16 v[146:161], v[106:109], v[190:193], v[146:161]
	v_mfma_f32_32x32x16_bf16 v[146:161], v[110:113], v[186:189], v[146:161]
	s_branch .Lattn_qkdone

; #define LAS __attribute__((address_space(3)))
; template <int MODE> ...
;     ...
;         } else if (interior) {
;             const LAS float* bp = btab + (t - kp0 - (32 * nt + 4 * half));
; #pragma unroll
;             for (int rg = 0; rg < 4; ++rg) { float bv[4];
; #pragma unroll
;                 for (int r4 = 0; r4 < 4; ++r4) bv[r4] = *(bp - (8 * rg + r4));
; #pragma unroll
;                 for (int r4 = 0; r4 < 4; ++r4) asm volatile("" : "+v"(bv[r4]));
; #pragma unroll
;                 for (int r4 = 0; r4 < 4; ++r4) { const int r = 4 * rg + r4; const float s2 = st[r] * SC + bv[r4]; st[r] = s2; mloc = fmaxf(mloc, s2); } }
;             if (!lanevalid) mloc = NEG_S;
.LBB0_2110:
	s_andn2_saveexec_b64 s[94:95], s[94:95]
	s_cbranch_execz .LBB0_2112
	v_add_u32_e32 v16, s26, v242
	v_sub_u32_e32 v16, v228, v16
	v_lshl_add_u32 v216, v16, 2, s58
	v_add_u32_e32 v216, 0x8794, v216
	ds_read2_b32 v[114:115], v216 offset0:26 offset1:27
	ds_read2_b32 v[116:117], v216 offset0:24 offset1:25
	ds_read2_b32 v[118:119], v216 offset0:18 offset1:19
	ds_read2_b32 v[120:121], v216 offset0:16 offset1:17
	ds_read2_b32 v[122:123], v216 offset0:10 offset1:11
	ds_read2_b32 v[124:125], v216 offset0:8 offset1:9
	ds_read2_b32 v[126:127], v216 offset0:2 offset1:3
	ds_read2_b32 v[128:129], v216 offset0:0 offset1:1
	s_waitcnt lgkmcnt(4)
	v_fma_f32 v16, v146, s82, v115
	v_fma_f32 v17, v147, s82, v114
	v_fma_f32 v206, v148, s82, v117
	v_fma_f32 v207, v149, s82, v116
	v_fma_f32 v210, v150, s82, v119
	v_fma_f32 v211, v151, s82, v118
	v_max3_f32 v146, v16, s55, v17
	v_fma_f32 v208, v152, s82, v121
	v_fma_f32 v209, v153, s82, v120
	v_max3_f32 v146, v146, v206, v207
	s_waitcnt lgkmcnt(0)
	v_fma_f32 v212, v154, s82, v123
	v_fma_f32 v213, v155, s82, v122
	v_max3_f32 v146, v146, v210, v211
	v_fma_f32 v214, v156, s82, v125
	v_fma_f32 v215, v157, s82, v124
	v_max3_f32 v146, v146, v208, v209
	v_fma_f32 v216, v158, s82, v127
	v_fma_f32 v217, v159, s82, v126
	v_max3_f32 v146, v146, v212, v213
	v_fma_f32 v218, v160, s82, v129
	v_fma_f32 v219, v161, s82, v128
	v_max3_f32 v146, v146, v214, v215
	v_max3_f32 v146, v146, v216, v217
	v_max3_f32 v146, v146, v218, v219
	v_cndmask_b32_e64 v246, v224, v146, s[74:75]

; #define LAS __attribute__((address_space(3)))
; __device__ __forceinline__ unsigned pk2(float lo, float hi) { const bfx2 b = __builtin_convertvector((f32x2){lo, hi}, bfx2); return __builtin_bit_cast(unsigned, b); }
; #define MFMA32(a, b, c) __builtin_amdgcn_mfma_f32_32x32x16_bf16((a), (b), (c), 0, 0, 0)
; template <int MODE> ...
;     ...
;         if (MODE == 0) {
;             mloc = fmaxf(mloc, __shfl_xor(mloc, 32));
;             const float mnew = mloc > m + 8.0f ? mloc : m;
;             if (__ballot(mnew != m) != 0ull) { const float alpha = __builtin_amdgcn_exp2f(m - mnew); m = mnew; l *= alpha;
; #pragma unroll
;                 for (int dt = 0; dt < 4; ++dt)
; #pragma unroll
;                     for (int i = 0; i < 16; ++i) ot[dt][i] *= alpha; }
;             float ls = 0.f; const float meff = lanevalid ? m : 3.0e30f;
; #pragma unroll
;             for (int r = 0; r < 16; ++r) { const float pv = __builtin_amdgcn_exp2f(st[r] - meff); st[r] = pv; ls += pv; }
;             l += ls;
; #pragma unroll
;             for (int s = 0; s < 2; ++s) {
;                 u32x4 pb; pb.x = pk2(st[8 * s + 0], st[8 * s + 1]); pb.y = pk2(st[8 * s + 2], st[8 * s + 3]); pb.z = pk2(st[8 * s + 4], st[8 * s + 5]); pb.w = pk2(st[8 * s + 6], st[8 * s + 7]);
;                 const bf16x8 bfrag = __builtin_bit_cast(bf16x8, pb);
;                 const LAS unsigned char* va = VT + ql * VT_PITCH + (32 * nt + 16 * s + 4 * half) * 2;
;                 s16x4 lo[4], hi[4];
; #pragma unroll
;                 for (int dt = 0; dt < 4; ++dt) { lo[dt] = *(const LAS s16x4*)(va + 32 * dt * VT_PITCH); hi[dt] = *(const LAS s16x4*)(va + 32 * dt * VT_PITCH + 16); }
; #pragma unroll
;                 for (int dt = 0; dt < 4; ++dt) { const bf16x8 afrag = __builtin_shufflevector(lo[dt], hi[dt], 0, 1, 2, 3, 4, 5, 6, 7); ot[dt] = MFMA32(afrag, bfrag, ot[dt]); }
;             }
.LBB0_2118:
	v_cndmask_b32_e64 v147, v225, v146, s[74:75]
	v_lshl_add_u32 v159, s63, 6, v244
	v_add_u32_e32 v156, 0x4000, v159
	v_add_u32_e32 v157, 0x5000, v159
	v_add_u32_e32 v158, 0x6000, v159
	v_add_u32_e32 v159, 0x7000, v159
	ds_read2_b64 v[114:117], v156 offset0:128 offset1:130
	ds_read2_b64 v[118:121], v157 offset0:160 offset1:162
	ds_read2_b64 v[122:125], v158 offset0:192 offset1:194
	ds_read2_b64 v[126:129], v159 offset0:224 offset1:226
	ds_read2_b64 v[130:133], v156 offset0:132 offset1:134
	ds_read2_b64 v[134:137], v157 offset0:164 offset1:166
	ds_read2_b64 v[138:141], v158 offset0:196 offset1:198
	ds_read2_b64 v[142:145], v159 offset0:228 offset1:230
	v_sub_f32_e32 v16, v16, v147
	v_sub_f32_e32 v17, v17, v147
	v_sub_f32_e32 v206, v206, v147
	v_sub_f32_e32 v207, v207, v147
	v_sub_f32_e32 v210, v210, v147
	v_sub_f32_e32 v211, v211, v147
	v_sub_f32_e32 v208, v208, v147
	v_sub_f32_e32 v209, v209, v147
	v_exp_f32_e32 v16, v16
	v_exp_f32_e32 v17, v17
	v_exp_f32_e32 v206, v206
	v_exp_f32_e32 v207, v207
	v_exp_f32_e32 v210, v210
	v_exp_f32_e32 v211, v211
	v_exp_f32_e32 v208, v208
	v_exp_f32_e32 v209, v209
	v_sub_f32_e32 v212, v212, v147
	v_cvt_pk_bf16_f32 v152, v16, v17
	v_cvt_pk_bf16_f32 v153, v206, v207
	v_cvt_pk_bf16_f32 v154, v210, v211
	v_cvt_pk_bf16_f32 v155, v208, v209
	v_sub_f32_e32 v213, v213, v147
	v_exp_f32_e32 v212, v212
	s_waitcnt lgkmcnt(6)
	v_mfma_f32_32x32x16_bf16 v[66:81], v[114:117], v[152:155], v[66:81]
	v_exp_f32_e32 v213, v213
	v_sub_f32_e32 v214, v214, v147
	v_exp_f32_e32 v214, v214
	v_sub_f32_e32 v215, v215, v147
	v_mfma_f32_32x32x16_bf16 v[50:65], v[118:121], v[152:155], v[50:65]
	v_exp_f32_e32 v215, v215
	v_sub_f32_e32 v216, v216, v147
	v_exp_f32_e32 v216, v216
	v_sub_f32_e32 v217, v217, v147
	s_waitcnt lgkmcnt(4)
	v_mfma_f32_32x32x16_bf16 v[34:49], v[122:125], v[152:155], v[34:49]
	v_exp_f32_e32 v217, v217
	v_sub_f32_e32 v218, v218, v147
	v_exp_f32_e32 v218, v218
	v_sub_f32_e32 v219, v219, v147
	v_mfma_f32_32x32x16_bf16 v[18:33], v[126:129], v[152:155], v[18:33]
	v_exp_f32_e32 v219, v219
	v_add_f32_e32 v16, 0, v16
	v_cvt_pk_bf16_f32 v148, v212, v213
	v_cvt_pk_bf16_f32 v149, v214, v215
	v_cvt_pk_bf16_f32 v150, v216, v217
	s_cmp_lg_u32 s63, 0
	s_cbranch_scc1 .Lattn_tail_b
	v_or_b32_e32 v160, 32, v227
	v_mad_u32_u24 v160, v160, s54, v2
	ds_read_b128 v[82:85], v160
	ds_read_b128 v[86:89], v160 offset:32
	ds_read_b128 v[90:93], v160 offset:64
	ds_read_b128 v[94:97], v160 offset:96
	ds_read_b128 v[98:101], v160 offset:128
	ds_read_b128 v[102:105], v160 offset:160
	ds_read_b128 v[106:109], v160 offset:192
	ds_read_b128 v[110:113], v160 offset:224
	v_add_f32_e32 v16, v17, v16
	v_add_f32_e32 v16, v206, v16
	v_cvt_pk_bf16_f32 v151, v218, v219
	v_add_f32_e32 v16, v207, v16
	v_add_f32_e32 v16, v210, v16
	s_waitcnt lgkmcnt(10)
	v_mfma_f32_32x32x16_bf16 v[66:81], v[130:133], v[148:151], v[66:81]
	v_add_f32_e32 v16, v211, v16
	v_add_f32_e32 v16, v208, v16
	v_add_f32_e32 v16, v209, v16
	v_add_f32_e32 v16, v212, v16
	v_mfma_f32_32x32x16_bf16 v[50:65], v[134:137], v[148:151], v[50:65]
	v_add_f32_e32 v16, v213, v16
	v_add_f32_e32 v16, v214, v16
	v_add_f32_e32 v16, v215, v16
	v_add_f32_e32 v16, v216, v16
	s_waitcnt lgkmcnt(8)
	v_mfma_f32_32x32x16_bf16 v[34:49], v[138:141], v[148:151], v[34:49]
	v_add_f32_e32 v16, v217, v16
	v_add_f32_e32 v16, v218, v16
	v_add_f32_e32 v16, v219, v16
	v_add_f32_e32 v243, v243, v16
	s_xor_b64 s[26:27], s[46:47], -1
	s_mov_b32 s63, 1
	s_andn2_b64 vcc, exec, s[26:27]
	s_mov_b64 s[46:47], 0
	v_mfma_f32_32x32x16_bf16 v[18:33], v[142:145], v[148:151], v[18:33]
	v_mov_b32_e32 v245, v146
	s_branch .LBB0_2107
.Lattn_tail_b:
	v_add_f32_e32 v16, v17, v16
	v_add_f32_e32 v16, v206, v16
	v_cvt_pk_bf16_f32 v151, v218, v219
	v_add_f32_e32 v16, v207, v16
	v_add_f32_e32 v16, v210, v16
	s_waitcnt lgkmcnt(2)
	v_mfma_f32_32x32x16_bf16 v[66:81], v[130:133], v[148:151], v[66:81]
	v_add_f32_e32 v16, v211, v16
	v_add_f32_e32 v16, v208, v16
	v_add_f32_e32 v16, v209, v16
	v_add_f32_e32 v16, v212, v16
	v_mfma_f32_32x32x16_bf16 v[50:65], v[134:137], v[148:151], v[50:65]
	v_add_f32_e32 v16, v213, v16
	v_add_f32_e32 v16, v214, v16
	v_add_f32_e32 v16, v215, v16
	v_add_f32_e32 v16, v216, v16
	s_waitcnt lgkmcnt(0)
	v_mfma_f32_32x32x16_bf16 v[34:49], v[138:141], v[148:151], v[34:49]
	v_add_f32_e32 v16, v217, v16
	v_add_f32_e32 v16, v218, v16
	v_add_f32_e32 v16, v219, v16
	v_add_f32_e32 v243, v243, v16
	s_xor_b64 s[26:27], s[46:47], -1
	s_mov_b32 s63, 1
	s_andn2_b64 vcc, exec, s[26:27]
	s_mov_b64 s[46:47], 0
	v_mfma_f32_32x32x16_bf16 v[18:33], v[142:145], v[148:151], v[18:33]
	s_branch .Lattn_m0_exit
